# LRU output stage: lane^1 partner sum via one DPP quad_perm move instead of index math + ds_bpermute
# speedup vs baseline: 1.0055x; 1.0050x over previous
.LBB0_363:
	v_bfe_u32 v80, v115, 5, 1
	v_and_b32_e32 v133, 31, v115
	v_lshlrev_b32_e32 v132, 8, v133
	v_lshlrev_b32_e32 v146, 4, v80
	v_lshlrev_b32_e32 v0, 4, v115
	v_and_b32_e32 v147, 0x70, v0
	v_add_u32_e32 v148, s90, v132
	v_lshlrev_b32_e32 v80, 7, v80
	v_or3_b32 v80, v80, s91, v133
	v_lshlrev_b32_e32 v80, 2, v80
	v_and_b32_e32 v132, 1, v115
	s_lshl_b32 s0, s24, 19
	s_waitcnt lgkmcnt(0)
	ds_read_b128 v[178:181], v234
	ds_read_b128 v[182:185], v238
	ds_read_b128 v[186:189], v238 offset:8192
	ds_read_b128 v[190:193], v235
	ds_read_b128 v[194:197], v239
	ds_read_b128 v[198:201], v239 offset:8192
	ds_read_b128 v[202:205], v236
	ds_read_b128 v[206:209], v151
	ds_read_b128 v[210:213], v151 offset:8192
	ds_read_b128 v[214:217], v237
	ds_read_b128 v[218:221], v176
	ds_read_b128 v[222:225], v176 offset:8192
	s_waitcnt lgkmcnt(11)
	s_waitcnt lgkmcnt(10)
	v_mfma_f32_32x32x16_f16 v[0:15], v[178:181], v[182:185], 0
	s_waitcnt lgkmcnt(9)
	v_mfma_f32_32x32x16_f16 v[16:31], v[178:181], v[186:189], 0
	ds_read_b128 v[226:229], v234 offset:128
	ds_read_b128 v[230:233], v238 offset:128
	ds_read_b128 v[134:137], v238 offset:8320
	s_waitcnt lgkmcnt(11)
	s_waitcnt lgkmcnt(10)
	v_mfma_f32_32x32x16_f16 v[0:15], v[190:193], v[194:197], v[0:15]
	s_waitcnt lgkmcnt(9)
	v_mfma_f32_32x32x16_f16 v[16:31], v[190:193], v[198:201], v[16:31]
	ds_read_b128 v[138:141], v235 offset:128
	ds_read_b128 v[142:145], v239 offset:128
	ds_read_b128 v[178:181], v239 offset:8320
	s_waitcnt lgkmcnt(11)
	s_waitcnt lgkmcnt(10)
	v_mfma_f32_32x32x16_f16 v[0:15], v[202:205], v[206:209], v[0:15]
	s_waitcnt lgkmcnt(9)
	v_mfma_f32_32x32x16_f16 v[16:31], v[202:205], v[210:213], v[16:31]
	ds_read_b128 v[182:185], v236 offset:128
	ds_read_b128 v[186:189], v151 offset:128
	ds_read_b128 v[190:193], v151 offset:8320
	s_waitcnt lgkmcnt(11)
	s_waitcnt lgkmcnt(10)
	v_mfma_f32_32x32x16_f16 v[0:15], v[214:217], v[218:221], v[0:15]
	s_waitcnt lgkmcnt(9)
	v_mfma_f32_32x32x16_f16 v[16:31], v[214:217], v[222:225], v[16:31]
	ds_read_b128 v[194:197], v237 offset:128
	ds_read_b128 v[198:201], v176 offset:128
	ds_read_b128 v[202:205], v176 offset:8320
	s_waitcnt lgkmcnt(11)
	s_waitcnt lgkmcnt(10)
	v_mfma_f32_32x32x16_f16 v[0:15], v[226:229], v[230:233], v[0:15]
	s_waitcnt lgkmcnt(9)
	v_mfma_f32_32x32x16_f16 v[16:31], v[226:229], v[134:137], v[16:31]
	s_waitcnt lgkmcnt(8)
	s_waitcnt lgkmcnt(7)
	v_mfma_f32_32x32x16_f16 v[0:15], v[138:141], v[142:145], v[0:15]
	s_waitcnt lgkmcnt(6)
	v_mfma_f32_32x32x16_f16 v[16:31], v[138:141], v[178:181], v[16:31]
	s_waitcnt lgkmcnt(5)
	s_waitcnt lgkmcnt(4)
	v_mfma_f32_32x32x16_f16 v[0:15], v[182:185], v[186:189], v[0:15]
	s_waitcnt lgkmcnt(3)
	v_mfma_f32_32x32x16_f16 v[16:31], v[182:185], v[190:193], v[16:31]
	s_waitcnt lgkmcnt(2)
	s_waitcnt lgkmcnt(1)
	v_mfma_f32_32x32x16_f16 v[0:15], v[194:197], v[198:201], v[0:15]
	s_waitcnt lgkmcnt(0)
	v_mfma_f32_32x32x16_f16 v[16:31], v[194:197], v[202:205], v[16:31]
	s_lshl_b32 s18, s3, 1
	s_add_i32 s19, s18, 32
	v_bitop3_b32 v134, v146, v147, s18 bitop3:0x36
	v_add_u32_e32 v134, v148, v134
	ds_read_b128 v[134:137], v134
	v_bitop3_b32 v138, v146, v147, s19 bitop3:0x36
	v_add_u32_e32 v138, v148, v138
	ds_read_b128 v[138:141], v138
	v_add_u32_e32 v250, s33, v80
	s_waitcnt lgkmcnt(1)
	v_mfma_f32_32x32x16_f16 v[152:167], v[134:137], v[168:171], 0
	s_waitcnt lgkmcnt(0)
	v_mfma_f32_32x32x16_f16 v[152:167], v[138:141], v[172:175], v[152:167]
	v_lshl_or_b32 v251, v132, 5, s0
	v_lshl_add_u32 v80, v114, 11, v251
	global_load_dwordx4 v[240:243], v80, s[22:23] offset:16
	global_load_dwordx4 v[244:247], v80, s[22:23]
	v_lshl_add_u64 v[248:249], s[22:23], 0, v[80:81]
	s_nop 4
	v_pk_fma_f32 v[0:1], v[0:1], s[56:57], v[108:109] op_sel_hi:[1,0,1] neg_lo:[1,0,0] neg_hi:[1,0,0]
	v_pk_fma_f32 v[4:5], v[4:5], s[56:57], v[108:109] op_sel_hi:[1,0,1] neg_lo:[1,0,0] neg_hi:[1,0,0]
	v_pk_fma_f32 v[8:9], v[8:9], s[56:57], v[108:109] op_sel_hi:[1,0,1] neg_lo:[1,0,0] neg_hi:[1,0,0]
	v_pk_fma_f32 v[12:13], v[12:13], s[56:57], v[108:109] op_sel_hi:[1,0,1] neg_lo:[1,0,0] neg_hi:[1,0,0]
	v_pk_fma_f32 v[16:17], v[16:17], s[56:57], v[110:111] op_sel_hi:[1,0,1] neg_lo:[1,0,0] neg_hi:[1,0,0]
	v_pk_fma_f32 v[20:21], v[20:21], s[56:57], v[110:111] op_sel_hi:[1,0,1] neg_lo:[1,0,0] neg_hi:[1,0,0]
	v_pk_fma_f32 v[24:25], v[24:25], s[56:57], v[110:111] op_sel_hi:[1,0,1] neg_lo:[1,0,0] neg_hi:[1,0,0]
	v_pk_fma_f32 v[28:29], v[28:29], s[56:57], v[110:111] op_sel_hi:[1,0,1] neg_lo:[1,0,0] neg_hi:[1,0,0]
	v_pk_fma_f32 v[18:19], v[18:19], s[56:57], v[110:111] op_sel_hi:[1,0,1] neg_lo:[1,0,0] neg_hi:[1,0,0]
	v_pk_fma_f32 v[22:23], v[22:23], s[56:57], v[110:111] op_sel_hi:[1,0,1] neg_lo:[1,0,0] neg_hi:[1,0,0]
	v_pk_fma_f32 v[26:27], v[26:27], s[56:57], v[110:111] op_sel_hi:[1,0,1] neg_lo:[1,0,0] neg_hi:[1,0,0]
	v_pk_fma_f32 v[30:31], v[30:31], s[56:57], v[110:111] op_sel_hi:[1,0,1] neg_lo:[1,0,0] neg_hi:[1,0,0]
	v_min_f32_e32 v191, 0x42700000, v0
	v_min_f32_e32 v205, 0x42700000, v4
	v_min_f32_e32 v219, 0x42700000, v8
	v_min_f32_e32 v233, 0x42700000, v12
	v_min_f32_e32 v1, 0x42700000, v1
	v_min_f32_e32 v5, 0x42700000, v5
	v_min_f32_e32 v9, 0x42700000, v9
	v_min_f32_e32 v13, 0x42700000, v13
	v_min_f32_e32 v181, 0x42700000, v16
	v_min_f32_e32 v195, 0x42700000, v20
	v_min_f32_e32 v209, 0x42700000, v24
	v_min_f32_e32 v223, 0x42700000, v28
	v_min_f32_e32 v182, 0x42700000, v17
	v_min_f32_e32 v196, 0x42700000, v21
	v_min_f32_e32 v210, 0x42700000, v25
	v_min_f32_e32 v224, 0x42700000, v29
	v_min_f32_e32 v190, 0x42700000, v18
	v_min_f32_e32 v204, 0x42700000, v22
	v_min_f32_e32 v218, 0x42700000, v26
	v_min_f32_e32 v232, 0x42700000, v30
	v_min_f32_e32 v183, 0x42700000, v19
	v_min_f32_e32 v197, 0x42700000, v23
	v_min_f32_e32 v211, 0x42700000, v27
	v_min_f32_e32 v225, 0x42700000, v31
	v_exp_f32_e32 v16, v191
	v_exp_f32_e32 v20, v205
	v_exp_f32_e32 v24, v219
	v_exp_f32_e32 v28, v233
	v_exp_f32_e32 v17, v1
	v_exp_f32_e32 v21, v5
	v_exp_f32_e32 v25, v9
	v_exp_f32_e32 v29, v13
	v_exp_f32_e32 v18, v181
	v_exp_f32_e32 v22, v195
	v_exp_f32_e32 v26, v209
	v_exp_f32_e32 v30, v223
	v_exp_f32_e32 v19, v182
	v_exp_f32_e32 v23, v196
	v_exp_f32_e32 v27, v210
	v_exp_f32_e32 v31, v224
	v_pk_fma_f32 v[2:3], v[2:3], s[56:57], v[108:109] op_sel_hi:[1,0,1] neg_lo:[1,0,0] neg_hi:[1,0,0]
	v_pk_fma_f32 v[6:7], v[6:7], s[56:57], v[108:109] op_sel_hi:[1,0,1] neg_lo:[1,0,0] neg_hi:[1,0,0]
	v_pk_fma_f32 v[10:11], v[10:11], s[56:57], v[108:109] op_sel_hi:[1,0,1] neg_lo:[1,0,0] neg_hi:[1,0,0]
	v_pk_fma_f32 v[14:15], v[14:15], s[56:57], v[108:109] op_sel_hi:[1,0,1] neg_lo:[1,0,0] neg_hi:[1,0,0]
	v_exp_f32_e32 v180, v190
	v_exp_f32_e32 v194, v204
	v_exp_f32_e32 v208, v218
	v_exp_f32_e32 v222, v232
	v_min_f32_e32 v190, 0x42700000, v2
	v_min_f32_e32 v204, 0x42700000, v6
	v_min_f32_e32 v218, 0x42700000, v10
	v_min_f32_e32 v232, 0x42700000, v14
	v_min_f32_e32 v191, 0x42700000, v3
	v_min_f32_e32 v205, 0x42700000, v7
	v_min_f32_e32 v219, 0x42700000, v11
	v_min_f32_e32 v233, 0x42700000, v15
	v_exp_f32_e32 v181, v183
	v_exp_f32_e32 v195, v197
	v_exp_f32_e32 v209, v211
	v_exp_f32_e32 v223, v225
	v_exp_f32_e32 v2, v190
	v_exp_f32_e32 v6, v204
	v_exp_f32_e32 v10, v218
	v_exp_f32_e32 v14, v232
	v_exp_f32_e32 v3, v191
	v_exp_f32_e32 v7, v205
	v_exp_f32_e32 v11, v219
	v_exp_f32_e32 v15, v233
	v_pk_add_f32 v[16:17], v[16:17], 1.0 op_sel_hi:[1,0]
	v_pk_add_f32 v[20:21], v[20:21], 1.0 op_sel_hi:[1,0]
	v_pk_add_f32 v[24:25], v[24:25], 1.0 op_sel_hi:[1,0]
	v_pk_add_f32 v[28:29], v[28:29], 1.0 op_sel_hi:[1,0]
	v_pk_add_f32 v[18:19], v[18:19], 1.0 op_sel_hi:[1,0]
	v_pk_add_f32 v[22:23], v[22:23], 1.0 op_sel_hi:[1,0]
	v_pk_add_f32 v[26:27], v[26:27], 1.0 op_sel_hi:[1,0]
	v_pk_add_f32 v[30:31], v[30:31], 1.0 op_sel_hi:[1,0]
	v_pk_add_f32 v[180:181], v[180:181], 1.0 op_sel_hi:[1,0]
	v_pk_add_f32 v[194:195], v[194:195], 1.0 op_sel_hi:[1,0]
	v_pk_add_f32 v[208:209], v[208:209], 1.0 op_sel_hi:[1,0]
	v_pk_add_f32 v[222:223], v[222:223], 1.0 op_sel_hi:[1,0]
	v_pk_mul_f32 v[182:183], v[16:17], v[18:19]
	v_pk_mul_f32 v[196:197], v[20:21], v[22:23]
	v_pk_mul_f32 v[210:211], v[24:25], v[26:27]
	v_pk_mul_f32 v[224:225], v[28:29], v[30:31]
	v_pk_add_f32 v[2:3], v[2:3], 1.0 op_sel_hi:[1,0]
	v_pk_add_f32 v[6:7], v[6:7], 1.0 op_sel_hi:[1,0]
	v_pk_add_f32 v[10:11], v[10:11], 1.0 op_sel_hi:[1,0]
	v_pk_add_f32 v[14:15], v[14:15], 1.0 op_sel_hi:[1,0]
	v_rcp_f32_e32 v182, v182
	v_rcp_f32_e32 v196, v196
	v_rcp_f32_e32 v210, v210
	v_rcp_f32_e32 v224, v224
	v_rcp_f32_e32 v183, v183
	v_rcp_f32_e32 v197, v197
	v_rcp_f32_e32 v211, v211
	v_rcp_f32_e32 v225, v225
	v_pk_mul_f32 v[184:185], v[2:3], v[180:181]
	v_pk_mul_f32 v[198:199], v[6:7], v[194:195]
	v_pk_mul_f32 v[212:213], v[10:11], v[208:209]
	v_pk_mul_f32 v[226:227], v[14:15], v[222:223]
	v_mov_b64_e32 v[178:179], s[64:65]
	v_mov_b64_e32 v[192:193], s[64:65]
	v_mov_b64_e32 v[206:207], s[64:65]
	v_mov_b64_e32 v[220:221], s[64:65]
	v_rcp_f32_e32 v184, v184
	v_rcp_f32_e32 v198, v198
	v_rcp_f32_e32 v212, v212
	v_rcp_f32_e32 v226, v226
	v_rcp_f32_e32 v185, v185
	v_rcp_f32_e32 v199, v199
	v_rcp_f32_e32 v213, v213
	v_rcp_f32_e32 v227, v227
	v_pk_mul_f32 v[18:19], v[18:19], v[182:183]
	v_pk_mul_f32 v[22:23], v[22:23], v[196:197]
	v_pk_mul_f32 v[26:27], v[26:27], v[210:211]
	v_pk_mul_f32 v[30:31], v[30:31], v[224:225]
	v_pk_mul_f32 v[16:17], v[16:17], v[182:183]
	v_pk_mul_f32 v[20:21], v[20:21], v[196:197]
	v_pk_mul_f32 v[24:25], v[24:25], v[210:211]
	v_pk_mul_f32 v[28:29], v[28:29], v[224:225]
	v_pk_mul_f32 v[182:183], v[106:107], v[18:19]
	v_pk_mul_f32 v[196:197], v[106:107], v[22:23]
	v_pk_mul_f32 v[210:211], v[106:107], v[26:27]
	v_pk_mul_f32 v[224:225], v[106:107], v[30:31]
	v_pk_mul_f32 v[18:19], v[112:113], v[18:19]
	v_pk_mul_f32 v[22:23], v[112:113], v[22:23]
	v_pk_mul_f32 v[26:27], v[112:113], v[26:27]
	v_pk_mul_f32 v[30:31], v[112:113], v[30:31]
	v_exp_f32_e32 v182, v182
	v_exp_f32_e32 v196, v196
	v_exp_f32_e32 v210, v210
	v_exp_f32_e32 v224, v224
	v_pk_fma_f32 v[186:187], v[18:19], s[62:63], v[178:179] op_sel_hi:[1,0,0]
	v_pk_fma_f32 v[200:201], v[22:23], s[62:63], v[192:193] op_sel_hi:[1,0,0]
	v_pk_fma_f32 v[214:215], v[26:27], s[62:63], v[206:207] op_sel_hi:[1,0,0]
	v_pk_fma_f32 v[228:229], v[30:31], s[62:63], v[220:221] op_sel_hi:[1,0,0]
	v_exp_f32_e32 v183, v183
	v_exp_f32_e32 v197, v197
	v_exp_f32_e32 v211, v211
	v_exp_f32_e32 v225, v225
	v_pk_mul_f32 v[180:181], v[180:181], v[184:185]
	v_pk_mul_f32 v[194:195], v[194:195], v[198:199]
	v_pk_mul_f32 v[208:209], v[208:209], v[212:213]
	v_pk_mul_f32 v[222:223], v[222:223], v[226:227]
	v_pk_mul_f32 v[2:3], v[2:3], v[184:185]
	v_pk_mul_f32 v[6:7], v[6:7], v[198:199]
	v_pk_mul_f32 v[10:11], v[10:11], v[212:213]
	v_pk_mul_f32 v[14:15], v[14:15], v[226:227]
	v_pk_fma_f32 v[184:185], v[18:19], v[186:187], s[66:67] op_sel_hi:[1,1,0]
	v_pk_fma_f32 v[198:199], v[22:23], v[200:201], s[66:67] op_sel_hi:[1,1,0]
	v_pk_fma_f32 v[212:213], v[26:27], v[214:215], s[66:67] op_sel_hi:[1,1,0]
	v_pk_fma_f32 v[226:227], v[30:31], v[228:229], s[66:67] op_sel_hi:[1,1,0]
	v_pk_mul_f32 v[186:187], v[106:107], v[180:181]
	v_pk_mul_f32 v[200:201], v[106:107], v[194:195]
	v_pk_mul_f32 v[214:215], v[106:107], v[208:209]
	v_pk_mul_f32 v[228:229], v[106:107], v[222:223]
	v_pk_fma_f32 v[184:185], v[18:19], v[184:185], s[68:69] op_sel_hi:[1,1,0]
	v_pk_fma_f32 v[198:199], v[22:23], v[198:199], s[68:69] op_sel_hi:[1,1,0]
	v_pk_fma_f32 v[212:213], v[26:27], v[212:213], s[68:69] op_sel_hi:[1,1,0]
	v_pk_fma_f32 v[226:227], v[30:31], v[226:227], s[68:69] op_sel_hi:[1,1,0]
	v_pk_mul_f32 v[180:181], v[112:113], v[180:181]
	v_pk_mul_f32 v[194:195], v[112:113], v[194:195]
	v_pk_mul_f32 v[208:209], v[112:113], v[208:209]
	v_pk_mul_f32 v[222:223], v[112:113], v[222:223]
	v_pk_fma_f32 v[184:185], v[18:19], v[184:185], 0.5 op_sel_hi:[1,1,0]
	v_pk_fma_f32 v[198:199], v[22:23], v[198:199], 0.5 op_sel_hi:[1,1,0]
	v_pk_fma_f32 v[212:213], v[26:27], v[212:213], 0.5 op_sel_hi:[1,1,0]
	v_pk_fma_f32 v[226:227], v[30:31], v[226:227], 0.5 op_sel_hi:[1,1,0]
	v_pk_fma_f32 v[178:179], v[180:181], s[62:63], v[178:179] op_sel_hi:[1,0,0]
	v_pk_fma_f32 v[192:193], v[194:195], s[62:63], v[192:193] op_sel_hi:[1,0,0]
	v_pk_fma_f32 v[206:207], v[208:209], s[62:63], v[206:207] op_sel_hi:[1,0,0]
	v_pk_fma_f32 v[220:221], v[222:223], s[62:63], v[220:221] op_sel_hi:[1,0,0]
	v_pk_fma_f32 v[184:185], v[18:19], v[184:185], 1.0 op_sel_hi:[1,1,0]
	v_pk_fma_f32 v[198:199], v[22:23], v[198:199], 1.0 op_sel_hi:[1,1,0]
	v_pk_fma_f32 v[212:213], v[26:27], v[212:213], 1.0 op_sel_hi:[1,1,0]
	v_pk_fma_f32 v[226:227], v[30:31], v[226:227], 1.0 op_sel_hi:[1,1,0]
	v_exp_f32_e32 v186, v186
	v_exp_f32_e32 v200, v200
	v_exp_f32_e32 v214, v214
	v_exp_f32_e32 v228, v228
	v_exp_f32_e32 v187, v187
	v_exp_f32_e32 v201, v201
	v_exp_f32_e32 v215, v215
	v_exp_f32_e32 v229, v229
	v_pk_fma_f32 v[178:179], v[180:181], v[178:179], s[66:67] op_sel_hi:[1,1,0]
	v_pk_fma_f32 v[192:193], v[194:195], v[192:193], s[66:67] op_sel_hi:[1,1,0]
	v_pk_fma_f32 v[206:207], v[208:209], v[206:207], s[66:67] op_sel_hi:[1,1,0]
	v_pk_fma_f32 v[220:221], v[222:223], v[220:221], s[66:67] op_sel_hi:[1,1,0]
	v_pk_fma_f32 v[188:189], v[182:183], v[182:183], 1.0 op_sel_hi:[1,1,0] neg_lo:[1,0,0] neg_hi:[1,0,0]
	v_pk_fma_f32 v[202:203], v[196:197], v[196:197], 1.0 op_sel_hi:[1,1,0] neg_lo:[1,0,0] neg_hi:[1,0,0]
	v_pk_fma_f32 v[216:217], v[210:211], v[210:211], 1.0 op_sel_hi:[1,1,0] neg_lo:[1,0,0] neg_hi:[1,0,0]
	v_pk_fma_f32 v[230:231], v[224:225], v[224:225], 1.0 op_sel_hi:[1,1,0] neg_lo:[1,0,0] neg_hi:[1,0,0]
	v_pk_mul_f32 v[184:185], v[18:19], v[184:185] neg_lo:[0,1] neg_hi:[0,1]
	v_pk_mul_f32 v[198:199], v[22:23], v[198:199] neg_lo:[0,1] neg_hi:[0,1]
	v_pk_mul_f32 v[212:213], v[26:27], v[212:213] neg_lo:[0,1] neg_hi:[0,1]
	v_pk_mul_f32 v[226:227], v[30:31], v[226:227] neg_lo:[0,1] neg_hi:[0,1]
	v_cmp_lt_f32_e64 s[16:17], s10, v19
	v_cmp_lt_f32_e64 s[18:19], s10, v18
	v_pk_fma_f32 v[178:179], v[180:181], v[178:179], s[68:69] op_sel_hi:[1,1,0]
	v_cndmask_b32_e64 v185, v189, v185, s[16:17]
	v_cndmask_b32_e64 v184, v188, v184, s[18:19]
	v_cmp_lt_f32_e64 s[16:17], s10, v23
	v_cmp_lt_f32_e64 s[18:19], s10, v22
	v_pk_fma_f32 v[192:193], v[194:195], v[192:193], s[68:69] op_sel_hi:[1,1,0]
	v_cndmask_b32_e64 v199, v203, v199, s[16:17]
	v_cndmask_b32_e64 v198, v202, v198, s[18:19]
	v_cmp_lt_f32_e64 s[16:17], s10, v27
	v_cmp_lt_f32_e64 s[18:19], s10, v26
	v_pk_fma_f32 v[206:207], v[208:209], v[206:207], s[68:69] op_sel_hi:[1,1,0]
	v_cndmask_b32_e64 v213, v217, v213, s[16:17]
	v_cndmask_b32_e64 v212, v216, v212, s[18:19]
	v_cmp_lt_f32_e64 s[16:17], s10, v31
	v_cmp_lt_f32_e64 s[18:19], s10, v30
	v_pk_fma_f32 v[220:221], v[222:223], v[220:221], s[68:69] op_sel_hi:[1,1,0]
	v_cndmask_b32_e64 v227, v231, v227, s[16:17]
	v_cndmask_b32_e64 v226, v230, v226, s[18:19]
	v_pk_fma_f32 v[178:179], v[180:181], v[178:179], 0.5 op_sel_hi:[1,1,0]
	v_pk_fma_f32 v[192:193], v[194:195], v[192:193], 0.5 op_sel_hi:[1,1,0]
	v_pk_fma_f32 v[206:207], v[208:209], v[206:207], 0.5 op_sel_hi:[1,1,0]
	v_pk_fma_f32 v[220:221], v[222:223], v[220:221], 0.5 op_sel_hi:[1,1,0]
	v_sqrt_f32_e32 v184, v184
	v_sqrt_f32_e32 v198, v198
	v_sqrt_f32_e32 v212, v212
	v_sqrt_f32_e32 v226, v226
	v_sqrt_f32_e32 v185, v185
	v_sqrt_f32_e32 v199, v199
	v_sqrt_f32_e32 v213, v213
	v_sqrt_f32_e32 v227, v227
	v_pk_fma_f32 v[178:179], v[180:181], v[178:179], 1.0 op_sel_hi:[1,1,0]
	v_pk_fma_f32 v[192:193], v[194:195], v[192:193], 1.0 op_sel_hi:[1,1,0]
	v_pk_fma_f32 v[206:207], v[208:209], v[206:207], 1.0 op_sel_hi:[1,1,0]
	v_pk_fma_f32 v[220:221], v[222:223], v[220:221], 1.0 op_sel_hi:[1,1,0]
	v_pk_fma_f32 v[18:19], v[186:187], v[186:187], 1.0 op_sel_hi:[1,1,0] neg_lo:[1,0,0] neg_hi:[1,0,0]
	v_pk_fma_f32 v[22:23], v[200:201], v[200:201], 1.0 op_sel_hi:[1,1,0] neg_lo:[1,0,0] neg_hi:[1,0,0]
	v_pk_fma_f32 v[26:27], v[214:215], v[214:215], 1.0 op_sel_hi:[1,1,0] neg_lo:[1,0,0] neg_hi:[1,0,0]
	v_pk_fma_f32 v[30:31], v[228:229], v[228:229], 1.0 op_sel_hi:[1,1,0] neg_lo:[1,0,0] neg_hi:[1,0,0]
	v_pk_mul_f32 v[178:179], v[180:181], v[178:179] neg_lo:[0,1] neg_hi:[0,1]
	v_pk_mul_f32 v[192:193], v[194:195], v[192:193] neg_lo:[0,1] neg_hi:[0,1]
	v_pk_mul_f32 v[206:207], v[208:209], v[206:207] neg_lo:[0,1] neg_hi:[0,1]
	v_pk_mul_f32 v[220:221], v[222:223], v[220:221] neg_lo:[0,1] neg_hi:[0,1]
	v_cmp_lt_f32_e64 s[16:17], s10, v181
	v_cmp_lt_f32_e64 s[18:19], s10, v180
	v_pk_mul_f32 v[16:17], v[16:17], v[184:185]
	v_cndmask_b32_e64 v179, v19, v179, s[16:17]
	v_cndmask_b32_e64 v178, v18, v178, s[18:19]
	v_cmp_lt_f32_e64 s[16:17], s10, v195
	v_cmp_lt_f32_e64 s[18:19], s10, v194
	v_pk_mul_f32 v[20:21], v[20:21], v[198:199]
	v_cndmask_b32_e64 v193, v23, v193, s[16:17]
	v_cndmask_b32_e64 v192, v22, v192, s[18:19]
	v_cmp_lt_f32_e64 s[16:17], s10, v209
	v_cmp_lt_f32_e64 s[18:19], s10, v208
	v_pk_mul_f32 v[24:25], v[24:25], v[212:213]
	v_cndmask_b32_e64 v207, v27, v207, s[16:17]
	v_cndmask_b32_e64 v206, v26, v206, s[18:19]
	v_cmp_lt_f32_e64 s[16:17], s10, v223
	v_cmp_lt_f32_e64 s[18:19], s10, v222
	v_pk_mul_f32 v[28:29], v[28:29], v[226:227]
	v_cndmask_b32_e64 v221, v31, v221, s[16:17]
	v_cndmask_b32_e64 v220, v30, v220, s[18:19]
	v_sqrt_f32_e32 v178, v178
	v_sqrt_f32_e32 v192, v192
	v_sqrt_f32_e32 v206, v206
	v_sqrt_f32_e32 v220, v220
	v_sqrt_f32_e32 v179, v179
	v_sqrt_f32_e32 v193, v193
	v_sqrt_f32_e32 v207, v207
	v_sqrt_f32_e32 v221, v221
	v_pk_mul_f32 v[16:17], v[152:153], v[16:17]
	v_pk_mul_f32 v[20:21], v[156:157], v[20:21]
	v_pk_mul_f32 v[24:25], v[160:161], v[24:25]
	v_pk_mul_f32 v[28:29], v[164:165], v[28:29]
	v_pk_mul_f32 v[178:179], v[2:3], v[178:179]
	v_pk_mul_f32 v[192:193], v[6:7], v[192:193]
	v_pk_mul_f32 v[206:207], v[10:11], v[206:207]
	v_pk_mul_f32 v[220:221], v[14:15], v[220:221]
	v_pk_mul_f32 v[178:179], v[154:155], v[178:179]
	v_pk_mul_f32 v[192:193], v[158:159], v[192:193]
	v_pk_mul_f32 v[206:207], v[162:163], v[206:207]
	v_pk_mul_f32 v[220:221], v[166:167], v[220:221]
	v_mul_f32_e32 v0, v182, v183
	v_fma_f32 v4, v183, v16, v17
	v_mul_f32_e32 v1, v196, v197
	v_fma_f32 v5, v197, v20, v21
	v_mul_f32_e32 v2, v210, v211
	v_fma_f32 v6, v211, v24, v25
	v_mul_f32_e32 v3, v224, v225
	v_fma_f32 v7, v225, v28, v29
	v_mul_f32_e32 v0, v0, v186
	v_fma_f32 v4, v186, v4, v178
	v_mul_f32_e32 v1, v1, v200
	v_fma_f32 v5, v200, v5, v192
	v_mul_f32_e32 v2, v2, v214
	v_fma_f32 v6, v214, v6, v206
	v_mul_f32_e32 v3, v3, v228
	v_fma_f32 v7, v228, v7, v220
	v_mul_f32_e32 v0, v0, v187
	v_fma_f32 v4, v187, v4, v179
	v_mul_f32_e32 v1, v1, v201
	v_fma_f32 v5, v201, v5, v193
	v_mul_f32_e32 v2, v2, v215
	v_fma_f32 v6, v215, v6, v207
	v_mul_f32_e32 v3, v3, v229
	v_fma_f32 v7, v229, v7, v221
	v_mov_b32_e32 v8, v0
	v_mov_b32_e32 v9, v1
	v_mov_b32_e32 v10, v2
	v_mov_b32_e32 v11, v3
	v_mov_b32_e32 v12, v4
	v_mov_b32_e32 v13, v5
	v_mov_b32_e32 v14, v6
	v_mov_b32_e32 v15, v7
	s_nop 1
	v_permlane32_swap_b32_e32 v0, v8
	v_permlane32_swap_b32_e32 v1, v9
	v_permlane32_swap_b32_e32 v2, v10
	v_permlane32_swap_b32_e32 v3, v11
	v_permlane32_swap_b32_e32 v4, v12
	v_permlane32_swap_b32_e32 v5, v13
	v_permlane32_swap_b32_e32 v6, v14
	v_permlane32_swap_b32_e32 v7, v15
	s_nop 0
	v_mov_b32_e32 v152, v0
	v_mov_b32_e32 v160, v4
	v_mul_f32_e32 v153, v8, v152
	v_fma_f32 v161, v8, v160, v12
	v_mul_f32_e32 v154, v1, v153
	v_fma_f32 v162, v1, v161, v5
	v_mul_f32_e32 v155, v9, v154
	v_fma_f32 v163, v9, v162, v13
	v_mul_f32_e32 v156, v2, v155
	v_fma_f32 v164, v2, v163, v6
	v_mul_f32_e32 v157, v10, v156
	v_fma_f32 v165, v10, v164, v14
	v_mul_f32_e32 v158, v3, v157
	v_fma_f32 v166, v3, v165, v7
	v_mul_f32_e32 v159, v11, v158
	v_fma_f32 v167, v11, v166, v15
	s_lshl_b32 s16, s24, 12
	s_and_b32 s16, s16, 0x1000
	s_add_i32 s16, s16, 0x20000
	s_lshr_b32 s17, s90, 5
	s_add_i32 s17, s17, s16
	v_lshl_add_u32 v251, v133, 2, s17
	v_lshl_add_u32 v177, v133, 2, s16
	ds_write2_b32 v251, v159, v167 offset1:32
	s_mov_b32 vcc_lo, 0
	s_mov_b32 vcc_hi, -1
	v_mov_b32_e32 v253, 1.0
	v_cndmask_b32_e32 v8, v253, v152, vcc
	v_cndmask_b32_e32 v12, 0, v160, vcc
	v_cndmask_b32_e32 v9, v153, v154, vcc
	v_cndmask_b32_e32 v13, v161, v162, vcc
	v_cndmask_b32_e32 v10, v155, v156, vcc
	v_cndmask_b32_e32 v14, v163, v164, vcc
	v_cndmask_b32_e32 v11, v157, v158, vcc
	v_cndmask_b32_e32 v15, v165, v166, vcc
	v_add_u32_e32 v253, 0x400, v177
	s_waitcnt lgkmcnt(0)
	s_barrier
	ds_read2_b32 v[152:153], v177 offset0:0 offset1:32
	ds_read2_b32 v[154:155], v177 offset0:64 offset1:96
	ds_read2_b32 v[156:157], v177 offset0:128 offset1:160
	ds_read2_b32 v[158:159], v177 offset0:192 offset1:224
	ds_read2_b32 v[160:161], v253 offset0:0 offset1:32
	ds_read2_b32 v[162:163], v253 offset0:64 offset1:96
	ds_read2_b32 v[164:165], v253 offset0:128 offset1:160
	ds_read2_b32 v[166:167], v253 offset0:192 offset1:224
	s_lshr_b32 s17, s90, 13
	v_mov_b32_e32 v251, v105
	s_cmp_eq_u32 s17, 0
	s_cselect_b64 s[18:19], -1, 0
	s_waitcnt lgkmcnt(7)
	v_cndmask_b32_e64 v251, v251, v105, s[18:19]
	v_fma_f32 v105, v152, v105, v153
	s_cmp_eq_u32 s17, 1
	s_cselect_b64 s[18:19], -1, 0
	s_waitcnt lgkmcnt(6)
	v_cndmask_b32_e64 v251, v251, v105, s[18:19]
	v_fma_f32 v105, v154, v105, v155
	s_cmp_eq_u32 s17, 2
	s_cselect_b64 s[18:19], -1, 0
	s_waitcnt lgkmcnt(5)
	v_cndmask_b32_e64 v251, v251, v105, s[18:19]
	v_fma_f32 v105, v156, v105, v157
	s_cmp_eq_u32 s17, 3
	s_cselect_b64 s[18:19], -1, 0
	s_waitcnt lgkmcnt(4)
	v_cndmask_b32_e64 v251, v251, v105, s[18:19]
	v_fma_f32 v105, v158, v105, v159
	s_cmp_eq_u32 s17, 4
	s_cselect_b64 s[18:19], -1, 0
	s_waitcnt lgkmcnt(3)
	v_cndmask_b32_e64 v251, v251, v105, s[18:19]
	v_fma_f32 v105, v160, v105, v161
	s_cmp_eq_u32 s17, 5
	s_cselect_b64 s[18:19], -1, 0
	s_waitcnt lgkmcnt(2)
	v_cndmask_b32_e64 v251, v251, v105, s[18:19]
	v_fma_f32 v105, v162, v105, v163
	s_cmp_eq_u32 s17, 6
	s_cselect_b64 s[18:19], -1, 0
	s_waitcnt lgkmcnt(1)
	v_cndmask_b32_e64 v251, v251, v105, s[18:19]
	v_fma_f32 v105, v164, v105, v165
	s_cmp_eq_u32 s17, 7
	s_cselect_b64 s[18:19], -1, 0
	s_waitcnt lgkmcnt(0)
	v_cndmask_b32_e64 v251, v251, v105, s[18:19]
	v_fma_f32 v105, v166, v105, v167
	v_fma_f32 v0, v8, v251, v12
	v_fma_f32 v1, v9, v251, v13
	v_fma_f32 v2, v10, v251, v14
	v_fma_f32 v3, v11, v251, v15
	v_fma_f32 v16, v182, v0, v16
	v_fma_f32 v20, v196, v1, v20
	v_fma_f32 v24, v210, v2, v24
	v_fma_f32 v28, v224, v3, v28
	v_fma_f32 v17, v183, v16, v17
	v_fma_f32 v21, v197, v20, v21
	v_fma_f32 v25, v211, v24, v25
	v_fma_f32 v29, v225, v28, v29
	v_fma_f32 v178, v186, v17, v178
	v_fma_f32 v192, v200, v21, v192
	v_fma_f32 v206, v214, v25, v206
	v_fma_f32 v220, v228, v29, v220
	v_fma_f32 v179, v187, v178, v179
	v_fma_f32 v193, v201, v192, v193
	v_fma_f32 v207, v215, v206, v207
	v_fma_f32 v221, v229, v220, v221
	ds_write_b32 v250, v16
	ds_write_b32 v250, v17 offset:128
	ds_write_b32 v250, v178 offset:256
	ds_write_b32 v250, v179 offset:384
	ds_write_b32 v250, v20 offset:1024
	ds_write_b32 v250, v21 offset:1152
	ds_write_b32 v250, v192 offset:1280
	ds_write_b32 v250, v193 offset:1408
	ds_write_b32 v250, v24 offset:2048
	ds_write_b32 v250, v25 offset:2176
	ds_write_b32 v250, v206 offset:2304
	ds_write_b32 v250, v207 offset:2432
	ds_write_b32 v250, v28 offset:3072
	ds_write_b32 v250, v29 offset:3200
	ds_write_b32 v250, v220 offset:3328
	ds_write_b32 v250, v221 offset:3456
	s_waitcnt lgkmcnt(0)
	v_lshlrev_b32_e32 v12, 7, v114
	v_lshlrev_b32_e32 v14, 6, v132
	s_waitcnt lgkmcnt(0)
	v_add3_u32 v12, s33, v12, v14
	ds_read_b128 v[14:17], v12
	ds_read_b128 v[18:21], v12 offset:16
	ds_read_b128 v[22:25], v12 offset:32
	ds_read_b128 v[26:29], v12 offset:48
	s_waitcnt lgkmcnt(3)
	v_mul_f32_e32 v12, v15, v15
	v_mul_f32_e32 v30, v17, v17
	v_fmac_f32_e32 v12, v14, v14
	v_fmac_f32_e32 v30, v16, v16
	v_add_f32_e32 v12, v12, v30
	s_waitcnt lgkmcnt(2)
	v_mul_f32_e32 v30, v19, v19
	v_fmac_f32_e32 v30, v18, v18
	v_add_f32_e32 v12, v12, v30
	v_mul_f32_e32 v30, v21, v21
	v_fmac_f32_e32 v30, v20, v20
	v_add_f32_e32 v12, v30, v12
	s_waitcnt lgkmcnt(1)
	v_mul_f32_e32 v30, v23, v23
	v_fmac_f32_e32 v30, v22, v22
	v_add_f32_e32 v12, v30, v12
	v_mul_f32_e32 v30, v25, v25
	v_fmac_f32_e32 v30, v24, v24
	v_add_f32_e32 v12, v30, v12
	s_waitcnt lgkmcnt(0)
	v_mul_f32_e32 v30, v27, v27
	v_fmac_f32_e32 v30, v26, v26
	v_add_f32_e32 v12, v30, v12
	v_mul_f32_e32 v30, v29, v29
	v_fmac_f32_e32 v30, v28, v28
	v_add_f32_e32 v12, v30, v12
	s_waitcnt vmcnt(0)
	v_lshlrev_b32_e32 v30, 16, v244
	v_and_b32_e32 v244, 0xffff0000, v244
	v_mul_f32_e32 v14, v14, v30
	v_mul_f32_e32 v244, v15, v244
	v_cvt_pk_bf16_f32 v244, v14, v244
	v_lshlrev_b32_e32 v14, 16, v245
	v_and_b32_e32 v245, 0xffff0000, v245
	v_mul_f32_e32 v14, v16, v14
	v_mul_f32_e32 v245, v17, v245
	v_cvt_pk_bf16_f32 v245, v14, v245
	v_lshlrev_b32_e32 v14, 16, v246
	v_and_b32_e32 v246, 0xffff0000, v246
	v_mul_f32_e32 v14, v18, v14
	v_mul_f32_e32 v246, v19, v246
	v_cvt_pk_bf16_f32 v246, v14, v246
	v_lshlrev_b32_e32 v14, 16, v247
	v_and_b32_e32 v247, 0xffff0000, v247
	v_mul_f32_e32 v14, v20, v14
	v_mul_f32_e32 v247, v21, v247
	v_cvt_pk_bf16_f32 v247, v14, v247
	v_lshlrev_b32_e32 v14, 16, v240
	v_and_b32_e32 v240, 0xffff0000, v240
	v_mul_f32_e32 v14, v22, v14
	v_mul_f32_e32 v240, v23, v240
	v_cvt_pk_bf16_f32 v14, v14, v240
	v_lshlrev_b32_e32 v240, 16, v241
	v_mul_f32_e32 v240, v24, v240
	v_and_b32_e32 v241, 0xffff0000, v241
	v_mul_f32_e32 v241, v25, v241
	v_cvt_pk_bf16_f32 v15, v240, v241
	v_lshlrev_b32_e32 v240, 16, v242
	v_mul_f32_e32 v240, v26, v240
	v_and_b32_e32 v241, 0xffff0000, v242
	v_mul_f32_e32 v241, v27, v241
	v_cvt_pk_bf16_f32 v16, v240, v241
	v_lshlrev_b32_e32 v240, 16, v243
	v_mul_f32_e32 v241, v28, v240
	v_and_b32_e32 v240, 0xffff0000, v243
	v_mul_f32_e32 v242, v29, v240
	v_cvt_pk_bf16_f32 v17, v241, v242
	global_store_dwordx4 v[248:249], v[244:247], off
	global_store_dwordx4 v[248:249], v[14:17], off offset:16
	v_mov_b32_dpp v240, v12 quad_perm:[1,0,3,2] row_mask:0xf bank_mask:0xf
	v_cmp_eq_u32_e64 s[16:17], 0, v132
	s_and_saveexec_b64 s[18:19], s[16:17]
	s_cbranch_execz .LBB0_360
	s_lshl_b64 s[0:1], s[52:53], 2
	s_add_u32 s0, s25, s0
	s_addc_u32 s1, s26, s1
	v_ashrrev_i32_e32 v115, 31, v114
	v_lshl_add_u64 v[242:243], v[114:115], 2, s[0:1]
	s_waitcnt lgkmcnt(0)
	v_add_f32_e32 v240, v12, v240
	global_store_dword v[242:243], v240, off
	s_branch .LBB0_360
